# BM selected-attention: interleave fp8 cvt lo/hi writes instead of s_nop padding, row-sum tail adds used as spacing before PV MFMAs
# baseline (speedup 1.0000x reference)
.Lbm2_Ag0_exp:
	v_exp_f32_e32 v84, v84
	v_exp_f32_e32 v85, v85
	v_exp_f32_e32 v86, v86
	v_exp_f32_e32 v87, v87
	v_exp_f32_e32 v88, v88
	v_exp_f32_e32 v89, v89
	v_exp_f32_e32 v90, v90
	v_exp_f32_e32 v91, v91
	v_exp_f32_e32 v92, v92
	v_exp_f32_e32 v93, v93
	v_exp_f32_e32 v94, v94
	v_exp_f32_e32 v95, v95
	v_exp_f32_e32 v96, v96
	v_exp_f32_e32 v97, v97
	v_exp_f32_e32 v98, v98
	v_exp_f32_e32 v99, v99
	v_pk_add_f32 v[248:249], v[84:85], v[86:87]
	v_pk_add_f32 v[248:249], v[248:249], v[88:89]
	v_pk_add_f32 v[248:249], v[248:249], v[90:91]
	v_pk_add_f32 v[248:249], v[248:249], v[92:93]
	v_pk_add_f32 v[248:249], v[248:249], v[94:95]
	v_pk_add_f32 v[248:249], v[248:249], v[96:97]
	v_pk_add_f32 v[248:249], v[248:249], v[98:99]
	v_cvt_pk_fp8_f32 v84, v84, v85
	v_cvt_pk_fp8_f32 v85, v88, v89
	v_cvt_pk_fp8_f32 v84, v86, v87 op_sel:[0,0,1]
	v_cvt_pk_fp8_f32 v85, v90, v91 op_sel:[0,0,1]
	v_cvt_pk_fp8_f32 v86, v92, v93
	v_cvt_pk_fp8_f32 v87, v96, v97
	v_cvt_pk_fp8_f32 v86, v94, v95 op_sel:[0,0,1]
	v_cvt_pk_fp8_f32 v87, v98, v99 op_sel:[0,0,1]
	v_add_f32_e32 v248, v248, v249
	v_add_f32_e32 v194, v194, v248
	s_waitcnt vmcnt(8)
	v_mfma_f32_16x16x32_fp8_fp8 v[100:103], v[36:37], v[84:85], v[100:103]
	v_mfma_f32_16x16x32_fp8_fp8 v[104:107], v[38:39], v[84:85], v[104:107]
	v_mfma_f32_16x16x32_fp8_fp8 v[108:111], v[40:41], v[84:85], v[108:111]
	v_mfma_f32_16x16x32_fp8_fp8 v[112:115], v[42:43], v[84:85], v[112:115]
	v_mfma_f32_16x16x32_fp8_fp8 v[100:103], v[44:45], v[86:87], v[100:103]
	v_mfma_f32_16x16x32_fp8_fp8 v[104:107], v[46:47], v[86:87], v[104:107]
	v_mfma_f32_16x16x32_fp8_fp8 v[108:111], v[48:49], v[86:87], v[108:111]
	v_mfma_f32_16x16x32_fp8_fp8 v[112:115], v[50:51], v[86:87], v[112:115]
	s_branch .Lbm2_Ag0_skip

.Lbm2_Ag1_exp:
	v_exp_f32_e32 v84, v84
	v_exp_f32_e32 v85, v85
	v_exp_f32_e32 v86, v86
	v_exp_f32_e32 v87, v87
	v_exp_f32_e32 v88, v88
	v_exp_f32_e32 v89, v89
	v_exp_f32_e32 v90, v90
	v_exp_f32_e32 v91, v91
	v_exp_f32_e32 v92, v92
	v_exp_f32_e32 v93, v93
	v_exp_f32_e32 v94, v94
	v_exp_f32_e32 v95, v95
	v_exp_f32_e32 v96, v96
	v_exp_f32_e32 v97, v97
	v_exp_f32_e32 v98, v98
	v_exp_f32_e32 v99, v99
	v_pk_add_f32 v[248:249], v[84:85], v[86:87]
	v_pk_add_f32 v[248:249], v[248:249], v[88:89]
	v_pk_add_f32 v[248:249], v[248:249], v[90:91]
	v_pk_add_f32 v[248:249], v[248:249], v[92:93]
	v_pk_add_f32 v[248:249], v[248:249], v[94:95]
	v_pk_add_f32 v[248:249], v[248:249], v[96:97]
	v_pk_add_f32 v[248:249], v[248:249], v[98:99]
	v_cvt_pk_fp8_f32 v84, v84, v85
	v_cvt_pk_fp8_f32 v85, v88, v89
	v_cvt_pk_fp8_f32 v84, v86, v87 op_sel:[0,0,1]
	v_cvt_pk_fp8_f32 v85, v90, v91 op_sel:[0,0,1]
	v_cvt_pk_fp8_f32 v86, v92, v93
	v_cvt_pk_fp8_f32 v87, v96, v97
	v_cvt_pk_fp8_f32 v86, v94, v95 op_sel:[0,0,1]
	v_cvt_pk_fp8_f32 v87, v98, v99 op_sel:[0,0,1]
	v_add_f32_e32 v248, v248, v249
	v_add_f32_e32 v195, v195, v248
	s_waitcnt vmcnt(8)
	v_mfma_f32_16x16x32_fp8_fp8 v[116:119], v[36:37], v[84:85], v[116:119]
	v_mfma_f32_16x16x32_fp8_fp8 v[120:123], v[38:39], v[84:85], v[120:123]
	v_mfma_f32_16x16x32_fp8_fp8 v[124:127], v[40:41], v[84:85], v[124:127]
	v_mfma_f32_16x16x32_fp8_fp8 v[128:131], v[42:43], v[84:85], v[128:131]
	v_mfma_f32_16x16x32_fp8_fp8 v[116:119], v[44:45], v[86:87], v[116:119]
	v_mfma_f32_16x16x32_fp8_fp8 v[120:123], v[46:47], v[86:87], v[120:123]
	v_mfma_f32_16x16x32_fp8_fp8 v[124:127], v[48:49], v[86:87], v[124:127]
	v_mfma_f32_16x16x32_fp8_fp8 v[128:131], v[50:51], v[86:87], v[128:131]
	s_branch .Lbm2_Ag1_skip

.Lbm2_Ag2_exp:
	v_exp_f32_e32 v84, v84
	v_exp_f32_e32 v85, v85
	v_exp_f32_e32 v86, v86
	v_exp_f32_e32 v87, v87
	v_exp_f32_e32 v88, v88
	v_exp_f32_e32 v89, v89
	v_exp_f32_e32 v90, v90
	v_exp_f32_e32 v91, v91
	v_exp_f32_e32 v92, v92
	v_exp_f32_e32 v93, v93
	v_exp_f32_e32 v94, v94
	v_exp_f32_e32 v95, v95
	v_exp_f32_e32 v96, v96
	v_exp_f32_e32 v97, v97
	v_exp_f32_e32 v98, v98
	v_exp_f32_e32 v99, v99
	v_pk_add_f32 v[248:249], v[84:85], v[86:87]
	v_pk_add_f32 v[248:249], v[248:249], v[88:89]
	v_pk_add_f32 v[248:249], v[248:249], v[90:91]
	v_pk_add_f32 v[248:249], v[248:249], v[92:93]
	v_pk_add_f32 v[248:249], v[248:249], v[94:95]
	v_pk_add_f32 v[248:249], v[248:249], v[96:97]
	v_pk_add_f32 v[248:249], v[248:249], v[98:99]
	v_cvt_pk_fp8_f32 v84, v84, v85
	v_cvt_pk_fp8_f32 v85, v88, v89
	v_cvt_pk_fp8_f32 v84, v86, v87 op_sel:[0,0,1]
	v_cvt_pk_fp8_f32 v85, v90, v91 op_sel:[0,0,1]
	v_cvt_pk_fp8_f32 v86, v92, v93
	v_cvt_pk_fp8_f32 v87, v96, v97
	v_cvt_pk_fp8_f32 v86, v94, v95 op_sel:[0,0,1]
	v_cvt_pk_fp8_f32 v87, v98, v99 op_sel:[0,0,1]
	v_add_f32_e32 v248, v248, v249
	v_add_f32_e32 v196, v196, v248
	s_waitcnt vmcnt(8)
	v_mfma_f32_16x16x32_fp8_fp8 v[132:135], v[36:37], v[84:85], v[132:135]
	v_mfma_f32_16x16x32_fp8_fp8 v[136:139], v[38:39], v[84:85], v[136:139]
	v_mfma_f32_16x16x32_fp8_fp8 v[140:143], v[40:41], v[84:85], v[140:143]
	v_mfma_f32_16x16x32_fp8_fp8 v[144:147], v[42:43], v[84:85], v[144:147]
	v_mfma_f32_16x16x32_fp8_fp8 v[132:135], v[44:45], v[86:87], v[132:135]
	v_mfma_f32_16x16x32_fp8_fp8 v[136:139], v[46:47], v[86:87], v[136:139]
	v_mfma_f32_16x16x32_fp8_fp8 v[140:143], v[48:49], v[86:87], v[140:143]
	v_mfma_f32_16x16x32_fp8_fp8 v[144:147], v[50:51], v[86:87], v[144:147]
	s_branch .Lbm2_Ag2_skip

.Lbm2_Ag3_exp:
	v_exp_f32_e32 v84, v84
	v_exp_f32_e32 v85, v85
	v_exp_f32_e32 v86, v86
	v_exp_f32_e32 v87, v87
	v_exp_f32_e32 v88, v88
	v_exp_f32_e32 v89, v89
	v_exp_f32_e32 v90, v90
	v_exp_f32_e32 v91, v91
	v_exp_f32_e32 v92, v92
	v_exp_f32_e32 v93, v93
	v_exp_f32_e32 v94, v94
	v_exp_f32_e32 v95, v95
	v_exp_f32_e32 v96, v96
	v_exp_f32_e32 v97, v97
	v_exp_f32_e32 v98, v98
	v_exp_f32_e32 v99, v99
	v_pk_add_f32 v[248:249], v[84:85], v[86:87]
	v_pk_add_f32 v[248:249], v[248:249], v[88:89]
	v_pk_add_f32 v[248:249], v[248:249], v[90:91]
	v_pk_add_f32 v[248:249], v[248:249], v[92:93]
	v_pk_add_f32 v[248:249], v[248:249], v[94:95]
	v_pk_add_f32 v[248:249], v[248:249], v[96:97]
	v_pk_add_f32 v[248:249], v[248:249], v[98:99]
	v_cvt_pk_fp8_f32 v84, v84, v85
	v_cvt_pk_fp8_f32 v85, v88, v89
	v_cvt_pk_fp8_f32 v84, v86, v87 op_sel:[0,0,1]
	v_cvt_pk_fp8_f32 v85, v90, v91 op_sel:[0,0,1]
	v_cvt_pk_fp8_f32 v86, v92, v93
	v_cvt_pk_fp8_f32 v87, v96, v97
	v_cvt_pk_fp8_f32 v86, v94, v95 op_sel:[0,0,1]
	v_cvt_pk_fp8_f32 v87, v98, v99 op_sel:[0,0,1]
	v_add_f32_e32 v248, v248, v249
	v_add_f32_e32 v197, v197, v248
	s_waitcnt vmcnt(8)
	v_mfma_f32_16x16x32_fp8_fp8 v[148:151], v[36:37], v[84:85], v[148:151]
	v_mfma_f32_16x16x32_fp8_fp8 v[152:155], v[38:39], v[84:85], v[152:155]
	v_mfma_f32_16x16x32_fp8_fp8 v[156:159], v[40:41], v[84:85], v[156:159]
	v_mfma_f32_16x16x32_fp8_fp8 v[160:163], v[42:43], v[84:85], v[160:163]
	v_mfma_f32_16x16x32_fp8_fp8 v[148:151], v[44:45], v[86:87], v[148:151]
	v_mfma_f32_16x16x32_fp8_fp8 v[152:155], v[46:47], v[86:87], v[152:155]
	v_mfma_f32_16x16x32_fp8_fp8 v[156:159], v[48:49], v[86:87], v[156:159]
	v_mfma_f32_16x16x32_fp8_fp8 v[160:163], v[50:51], v[86:87], v[160:163]
	s_branch .Lbm2_Ag3_skip

.Lbm2_Bg0_exp:
	v_exp_f32_e32 v84, v84
	v_exp_f32_e32 v85, v85
	v_exp_f32_e32 v86, v86
	v_exp_f32_e32 v87, v87
	v_exp_f32_e32 v88, v88
	v_exp_f32_e32 v89, v89
	v_exp_f32_e32 v90, v90
	v_exp_f32_e32 v91, v91
	v_exp_f32_e32 v92, v92
	v_exp_f32_e32 v93, v93
	v_exp_f32_e32 v94, v94
	v_exp_f32_e32 v95, v95
	v_exp_f32_e32 v96, v96
	v_exp_f32_e32 v97, v97
	v_exp_f32_e32 v98, v98
	v_exp_f32_e32 v99, v99
	v_pk_add_f32 v[248:249], v[84:85], v[86:87]
	v_pk_add_f32 v[248:249], v[248:249], v[88:89]
	v_pk_add_f32 v[248:249], v[248:249], v[90:91]
	v_pk_add_f32 v[248:249], v[248:249], v[92:93]
	v_pk_add_f32 v[248:249], v[248:249], v[94:95]
	v_pk_add_f32 v[248:249], v[248:249], v[96:97]
	v_pk_add_f32 v[248:249], v[248:249], v[98:99]
	v_cvt_pk_fp8_f32 v84, v84, v85
	v_cvt_pk_fp8_f32 v85, v88, v89
	v_cvt_pk_fp8_f32 v84, v86, v87 op_sel:[0,0,1]
	v_cvt_pk_fp8_f32 v85, v90, v91 op_sel:[0,0,1]
	v_cvt_pk_fp8_f32 v86, v92, v93
	v_cvt_pk_fp8_f32 v87, v96, v97
	v_cvt_pk_fp8_f32 v86, v94, v95 op_sel:[0,0,1]
	v_cvt_pk_fp8_f32 v87, v98, v99 op_sel:[0,0,1]
	v_add_f32_e32 v248, v248, v249
	v_add_f32_e32 v194, v194, v248
	s_waitcnt vmcnt(8)
	v_mfma_f32_16x16x32_fp8_fp8 v[100:103], v[52:53], v[84:85], v[100:103]
	v_mfma_f32_16x16x32_fp8_fp8 v[104:107], v[54:55], v[84:85], v[104:107]
	v_mfma_f32_16x16x32_fp8_fp8 v[108:111], v[56:57], v[84:85], v[108:111]
	v_mfma_f32_16x16x32_fp8_fp8 v[112:115], v[58:59], v[84:85], v[112:115]
	v_mfma_f32_16x16x32_fp8_fp8 v[100:103], v[60:61], v[86:87], v[100:103]
	v_mfma_f32_16x16x32_fp8_fp8 v[104:107], v[62:63], v[86:87], v[104:107]
	v_mfma_f32_16x16x32_fp8_fp8 v[108:111], v[64:65], v[86:87], v[108:111]
	v_mfma_f32_16x16x32_fp8_fp8 v[112:115], v[66:67], v[86:87], v[112:115]
	s_branch .Lbm2_Bg0_skip

.Lbm2_Bg1_exp:
	v_exp_f32_e32 v84, v84
	v_exp_f32_e32 v85, v85
	v_exp_f32_e32 v86, v86
	v_exp_f32_e32 v87, v87
	v_exp_f32_e32 v88, v88
	v_exp_f32_e32 v89, v89
	v_exp_f32_e32 v90, v90
	v_exp_f32_e32 v91, v91
	v_exp_f32_e32 v92, v92
	v_exp_f32_e32 v93, v93
	v_exp_f32_e32 v94, v94
	v_exp_f32_e32 v95, v95
	v_exp_f32_e32 v96, v96
	v_exp_f32_e32 v97, v97
	v_exp_f32_e32 v98, v98
	v_exp_f32_e32 v99, v99
	v_pk_add_f32 v[248:249], v[84:85], v[86:87]
	v_pk_add_f32 v[248:249], v[248:249], v[88:89]
	v_pk_add_f32 v[248:249], v[248:249], v[90:91]
	v_pk_add_f32 v[248:249], v[248:249], v[92:93]
	v_pk_add_f32 v[248:249], v[248:249], v[94:95]
	v_pk_add_f32 v[248:249], v[248:249], v[96:97]
	v_pk_add_f32 v[248:249], v[248:249], v[98:99]
	v_cvt_pk_fp8_f32 v84, v84, v85
	v_cvt_pk_fp8_f32 v85, v88, v89
	v_cvt_pk_fp8_f32 v84, v86, v87 op_sel:[0,0,1]
	v_cvt_pk_fp8_f32 v85, v90, v91 op_sel:[0,0,1]
	v_cvt_pk_fp8_f32 v86, v92, v93
	v_cvt_pk_fp8_f32 v87, v96, v97
	v_cvt_pk_fp8_f32 v86, v94, v95 op_sel:[0,0,1]
	v_cvt_pk_fp8_f32 v87, v98, v99 op_sel:[0,0,1]
	v_add_f32_e32 v248, v248, v249
	v_add_f32_e32 v195, v195, v248
	s_waitcnt vmcnt(8)
	v_mfma_f32_16x16x32_fp8_fp8 v[116:119], v[52:53], v[84:85], v[116:119]
	v_mfma_f32_16x16x32_fp8_fp8 v[120:123], v[54:55], v[84:85], v[120:123]
	v_mfma_f32_16x16x32_fp8_fp8 v[124:127], v[56:57], v[84:85], v[124:127]
	v_mfma_f32_16x16x32_fp8_fp8 v[128:131], v[58:59], v[84:85], v[128:131]
	v_mfma_f32_16x16x32_fp8_fp8 v[116:119], v[60:61], v[86:87], v[116:119]
	v_mfma_f32_16x16x32_fp8_fp8 v[120:123], v[62:63], v[86:87], v[120:123]
	v_mfma_f32_16x16x32_fp8_fp8 v[124:127], v[64:65], v[86:87], v[124:127]
	v_mfma_f32_16x16x32_fp8_fp8 v[128:131], v[66:67], v[86:87], v[128:131]
	s_branch .Lbm2_Bg1_skip

.Lbm2_Bg2_exp:
	v_exp_f32_e32 v84, v84
	v_exp_f32_e32 v85, v85
	v_exp_f32_e32 v86, v86
	v_exp_f32_e32 v87, v87
	v_exp_f32_e32 v88, v88
	v_exp_f32_e32 v89, v89
	v_exp_f32_e32 v90, v90
	v_exp_f32_e32 v91, v91
	v_exp_f32_e32 v92, v92
	v_exp_f32_e32 v93, v93
	v_exp_f32_e32 v94, v94
	v_exp_f32_e32 v95, v95
	v_exp_f32_e32 v96, v96
	v_exp_f32_e32 v97, v97
	v_exp_f32_e32 v98, v98
	v_exp_f32_e32 v99, v99
	v_pk_add_f32 v[248:249], v[84:85], v[86:87]
	v_pk_add_f32 v[248:249], v[248:249], v[88:89]
	v_pk_add_f32 v[248:249], v[248:249], v[90:91]
	v_pk_add_f32 v[248:249], v[248:249], v[92:93]
	v_pk_add_f32 v[248:249], v[248:249], v[94:95]
	v_pk_add_f32 v[248:249], v[248:249], v[96:97]
	v_pk_add_f32 v[248:249], v[248:249], v[98:99]
	v_cvt_pk_fp8_f32 v84, v84, v85
	v_cvt_pk_fp8_f32 v85, v88, v89
	v_cvt_pk_fp8_f32 v84, v86, v87 op_sel:[0,0,1]
	v_cvt_pk_fp8_f32 v85, v90, v91 op_sel:[0,0,1]
	v_cvt_pk_fp8_f32 v86, v92, v93
	v_cvt_pk_fp8_f32 v87, v96, v97
	v_cvt_pk_fp8_f32 v86, v94, v95 op_sel:[0,0,1]
	v_cvt_pk_fp8_f32 v87, v98, v99 op_sel:[0,0,1]
	v_add_f32_e32 v248, v248, v249
	v_add_f32_e32 v196, v196, v248
	s_waitcnt vmcnt(8)
	v_mfma_f32_16x16x32_fp8_fp8 v[132:135], v[52:53], v[84:85], v[132:135]
	v_mfma_f32_16x16x32_fp8_fp8 v[136:139], v[54:55], v[84:85], v[136:139]
	v_mfma_f32_16x16x32_fp8_fp8 v[140:143], v[56:57], v[84:85], v[140:143]
	v_mfma_f32_16x16x32_fp8_fp8 v[144:147], v[58:59], v[84:85], v[144:147]
	v_mfma_f32_16x16x32_fp8_fp8 v[132:135], v[60:61], v[86:87], v[132:135]
	v_mfma_f32_16x16x32_fp8_fp8 v[136:139], v[62:63], v[86:87], v[136:139]
	v_mfma_f32_16x16x32_fp8_fp8 v[140:143], v[64:65], v[86:87], v[140:143]
	v_mfma_f32_16x16x32_fp8_fp8 v[144:147], v[66:67], v[86:87], v[144:147]
	s_branch .Lbm2_Bg2_skip

.Lbm2_Bg3_exp:
	v_exp_f32_e32 v84, v84
	v_exp_f32_e32 v85, v85
	v_exp_f32_e32 v86, v86
	v_exp_f32_e32 v87, v87
	v_exp_f32_e32 v88, v88
	v_exp_f32_e32 v89, v89
	v_exp_f32_e32 v90, v90
	v_exp_f32_e32 v91, v91
	v_exp_f32_e32 v92, v92
	v_exp_f32_e32 v93, v93
	v_exp_f32_e32 v94, v94
	v_exp_f32_e32 v95, v95
	v_exp_f32_e32 v96, v96
	v_exp_f32_e32 v97, v97
	v_exp_f32_e32 v98, v98
	v_exp_f32_e32 v99, v99
	v_pk_add_f32 v[248:249], v[84:85], v[86:87]
	v_pk_add_f32 v[248:249], v[248:249], v[88:89]
	v_pk_add_f32 v[248:249], v[248:249], v[90:91]
	v_pk_add_f32 v[248:249], v[248:249], v[92:93]
	v_pk_add_f32 v[248:249], v[248:249], v[94:95]
	v_pk_add_f32 v[248:249], v[248:249], v[96:97]
	v_pk_add_f32 v[248:249], v[248:249], v[98:99]
	v_cvt_pk_fp8_f32 v84, v84, v85
	v_cvt_pk_fp8_f32 v85, v88, v89
	v_cvt_pk_fp8_f32 v84, v86, v87 op_sel:[0,0,1]
	v_cvt_pk_fp8_f32 v85, v90, v91 op_sel:[0,0,1]
	v_cvt_pk_fp8_f32 v86, v92, v93
	v_cvt_pk_fp8_f32 v87, v96, v97
	v_cvt_pk_fp8_f32 v86, v94, v95 op_sel:[0,0,1]
	v_cvt_pk_fp8_f32 v87, v98, v99 op_sel:[0,0,1]
	v_add_f32_e32 v248, v248, v249
	v_add_f32_e32 v197, v197, v248
	s_waitcnt vmcnt(8)
	v_mfma_f32_16x16x32_fp8_fp8 v[148:151], v[52:53], v[84:85], v[148:151]
	v_mfma_f32_16x16x32_fp8_fp8 v[152:155], v[54:55], v[84:85], v[152:155]
	v_mfma_f32_16x16x32_fp8_fp8 v[156:159], v[56:57], v[84:85], v[156:159]
	v_mfma_f32_16x16x32_fp8_fp8 v[160:163], v[58:59], v[84:85], v[160:163]
	v_mfma_f32_16x16x32_fp8_fp8 v[148:151], v[60:61], v[86:87], v[148:151]
	v_mfma_f32_16x16x32_fp8_fp8 v[152:155], v[62:63], v[86:87], v[152:155]
	v_mfma_f32_16x16x32_fp8_fp8 v[156:159], v[64:65], v[86:87], v[156:159]
	v_mfma_f32_16x16x32_fp8_fp8 v[160:163], v[66:67], v[86:87], v[160:163]
	s_branch .Lbm2_Bg3_skip
